# pre-MLP rmsnorm: next row prefetched into a second register set (2x unrolled, counted waits); long layer-loop branches routed via mid-file trampolines
# speedup vs baseline: 1.0087x; 1.0036x over previous
.Ltramp_16:
	s_branch .LBB0_16

.LBB0_943:
	s_cmp_le_i32 s58, s40
	s_cselect_b64 s[0:1], -1, 0
	s_and_b64 s[4:5], s[0:1], s[44:45]
	s_andn2_b64 vcc, exec, s[4:5]
	s_cbranch_vccnz .LBB0_947
	s_mov_b32 s4, s80
	v_mbcnt_lo_u32_b32 v0, -1, 0
	v_mbcnt_hi_u32_b32 v0, -1, v0
	s_add_i32 s4, s4, s81
	s_mov_b64 s[6:7], s[56:57]
	s_cmpk_gt_i32 s4, 0x7fff
	s_cbranch_scc1 .LBB0_947
	s_waitcnt vmcnt(0) lgkmcnt(0)
	v_mov_b64_e32 v[2:3], s[6:7]
	global_load_dwordx2 v[4:5], v[2:3], off offset:176
	global_load_dwordx4 v[18:21], v[2:3], off offset:208
	v_readlane_b32 s6, v255, 10
	v_lshlrev_b32_e32 v22, 3, v0
	s_lshl_b32 s74, s6, 10
	v_ashrrev_i32_e32 v23, 31, v22
	v_lshlrev_b64 v[24:25], 2, v[22:23]
	v_readlane_b32 s7, v255, 11
	s_ashr_i32 s5, s4, 31
	s_lshl_b64 s[6:7], s[4:5], 11
	v_lshl_add_u64 v[22:23], v[22:23], 1, s[6:7]
	v_lshlrev_b32_e32 v26, 2, v0
	s_mov_b64 s[6:7], 0x2b89400
	v_xor_b32_e32 v0, 0x80, v26
	v_xor_b32_e32 v30, 64, v26
	v_xor_b32_e32 v31, 32, v26
	v_xor_b32_e32 v32, 16, v26
	v_xor_b32_e32 v33, 8, v26
	v_xor_b32_e32 v34, 4, v26
	s_waitcnt vmcnt(0) lgkmcnt(0)
	v_lshl_add_u64 v[2:3], s[74:75], 2, v[4:5]
	v_lshl_add_u64 v[14:15], v[2:3], 0, v[24:25]
	global_load_dwordx4 v[2:5], v[14:15], off
	global_load_dwordx4 v[6:9], v[14:15], off offset:16
	global_load_dwordx4 v[10:13], v[14:15], off offset:2048
	s_nop 0
	global_load_dwordx4 v[14:17], v[14:15], off offset:2064
	v_lshl_add_u64 v[20:21], v[20:21], 0, v[22:23]
	v_lshl_add_u64 v[26:27], v[20:21], 0, s[6:7]
	s_lshl_b64 s[6:7], s[4:5], 12
	v_lshl_add_u64 v[20:21], s[6:7], 0, v[24:25]
	v_lshl_add_u64 v[28:29], v[18:19], 0, v[20:21]
	global_load_dwordx4 v[36:39], v[28:29], off
	global_load_dwordx4 v[40:43], v[28:29], off offset:16
	global_load_dwordx4 v[22:25], v[28:29], off offset:2048
	global_load_dwordx4 v[18:21], v[28:29], off offset:2064
.LBB0_946:
	s_add_i32 s4, s4, s38
	s_cmp_lt_i32 s4, 0x8000
	s_cselect_b32 s100, s46, 0
	s_cselect_b32 s101, s47, 0
	v_lshl_add_u64 v[28:29], v[28:29], 0, s[100:101]
	global_load_dwordx4 v[52:55], v[28:29], off
	global_load_dwordx4 v[56:59], v[28:29], off offset:16
	global_load_dwordx4 v[60:63], v[28:29], off offset:2048
	global_load_dwordx4 v[64:67], v[28:29], off offset:2064
	s_waitcnt vmcnt(4)
	v_mov_b32_e32 v68, v37
	v_mov_b32_e32 v69, v41
	v_mov_b32_e32 v70, v36
	v_mov_b32_e32 v71, v40
	v_pk_mul_f32 v[68:69], v[68:69], v[68:69]
	s_nop 0
	v_pk_fma_f32 v[70:71], v[70:71], v[70:71], v[68:69]
	v_mov_b32_e32 v68, v38
	v_mov_b32_e32 v69, v42
	v_pk_fma_f32 v[70:71], v[68:69], v[68:69], v[70:71]
	v_mov_b32_e32 v68, v39
	v_mov_b32_e32 v69, v43
	v_pk_fma_f32 v[44:45], v[68:69], v[68:69], v[70:71]
	s_nop 0
	v_add_f32_e32 v35, v44, v45
	v_mov_b32_e32 v48, v23
	v_mov_b32_e32 v49, v19
	v_mov_b32_e32 v46, v22
	v_mov_b32_e32 v47, v18
	v_pk_mul_f32 v[48:49], v[48:49], v[48:49]
	s_nop 0
	v_pk_fma_f32 v[46:47], v[46:47], v[46:47], v[48:49]
	v_mov_b32_e32 v48, v24
	v_mov_b32_e32 v49, v20
	v_pk_fma_f32 v[46:47], v[48:49], v[48:49], v[46:47]
	v_mov_b32_e32 v48, v25
	v_mov_b32_e32 v49, v21
	v_pk_fma_f32 v[46:47], v[48:49], v[48:49], v[46:47]
	s_nop 0
	v_add_f32_e32 v35, v35, v46
	v_add_f32_e32 v35, v35, v47
	ds_bpermute_b32 v44, v0, v35
	s_waitcnt lgkmcnt(0)
	v_add_f32_e32 v35, v35, v44
	ds_bpermute_b32 v44, v30, v35
	s_waitcnt lgkmcnt(0)
	v_add_f32_e32 v35, v35, v44
	ds_bpermute_b32 v44, v31, v35
	s_waitcnt lgkmcnt(0)
	v_add_f32_e32 v35, v35, v44
	ds_bpermute_b32 v44, v32, v35
	s_waitcnt lgkmcnt(0)
	v_add_f32_e32 v35, v35, v44
	ds_bpermute_b32 v44, v33, v35
	s_waitcnt lgkmcnt(0)
	v_add_f32_e32 v35, v35, v44
	ds_bpermute_b32 v44, v34, v35
	s_waitcnt lgkmcnt(0)
	v_add_f32_e32 v35, v35, v44
	v_fmamk_f32 v35, v35, 0x3a800000, v244
	v_cmp_gt_f32_e32 vcc, s82, v35
	v_mul_f32_e32 v44, 0x4b800000, v35
	s_nop 0
	v_cndmask_b32_e32 v35, v35, v44, vcc
	v_rsq_f32_e32 v35, v35
	s_nop 0
	v_mul_f32_e32 v44, 0x45800000, v35
	v_cndmask_b32_e32 v44, v35, v44, vcc
	v_pk_mul_f32 v[36:37], v[36:37], v[44:45] op_sel_hi:[1,0]
	v_pk_mul_f32 v[38:39], v[38:39], v[44:45] op_sel_hi:[1,0]
	v_pk_mul_f32 v[40:41], v[40:41], v[44:45] op_sel_hi:[1,0]
	v_pk_mul_f32 v[42:43], v[42:43], v[44:45] op_sel_hi:[1,0]
	v_pk_mul_f32 v[22:23], v[22:23], v[44:45] op_sel_hi:[1,0]
	v_pk_mul_f32 v[24:25], v[24:25], v[44:45] op_sel_hi:[1,0]
	v_pk_mul_f32 v[18:19], v[18:19], v[44:45] op_sel_hi:[1,0]
	v_pk_mul_f32 v[20:21], v[20:21], v[44:45] op_sel_hi:[1,0]
	v_pk_mul_f32 v[36:37], v[2:3], v[36:37]
	v_pk_mul_f32 v[38:39], v[4:5], v[38:39]
	v_pk_mul_f32 v[40:41], v[6:7], v[40:41]
	v_pk_mul_f32 v[42:43], v[8:9], v[42:43]
	v_pk_mul_f32 v[22:23], v[10:11], v[22:23]
	v_pk_mul_f32 v[24:25], v[12:13], v[24:25]
	v_pk_mul_f32 v[18:19], v[14:15], v[18:19]
	v_pk_mul_f32 v[20:21], v[16:17], v[20:21]
	v_cvt_pk_bf16_f32 v36, v36, v37
	v_cvt_pk_bf16_f32 v37, v38, v39
	v_cvt_pk_bf16_f32 v38, v40, v41
	v_cvt_pk_bf16_f32 v39, v42, v43
	v_cvt_pk_bf16_f32 v22, v22, v23
	v_cvt_pk_bf16_f32 v23, v24, v25
	v_cvt_pk_bf16_f32 v24, v18, v19
	v_cvt_pk_bf16_f32 v25, v20, v21
	v_add_co_u32_e32 v72, vcc, s83, v26
	s_nop 0
	v_addc_co_u32_e32 v73, vcc, -1, v27, vcc
	global_store_dwordx4 v[72:73], v[36:39], off
	global_store_dwordx4 v[26:27], v[22:25], off
	v_lshl_add_u64 v[26:27], v[26:27], 0, s[68:69]
	s_cbranch_scc0 .Lrn8_exit
	s_add_i32 s4, s4, s38
	s_cmp_lt_i32 s4, 0x8000
	s_cselect_b32 s100, s46, 0
	s_cselect_b32 s101, s47, 0
	v_lshl_add_u64 v[28:29], v[28:29], 0, s[100:101]
	global_load_dwordx4 v[36:39], v[28:29], off
	global_load_dwordx4 v[40:43], v[28:29], off offset:16
	global_load_dwordx4 v[22:25], v[28:29], off offset:2048
	global_load_dwordx4 v[18:21], v[28:29], off offset:2064
	s_waitcnt vmcnt(6)
	v_mov_b32_e32 v68, v53
	v_mov_b32_e32 v69, v57
	v_mov_b32_e32 v70, v52
	v_mov_b32_e32 v71, v56
	v_pk_mul_f32 v[68:69], v[68:69], v[68:69]
	s_nop 0
	v_pk_fma_f32 v[70:71], v[70:71], v[70:71], v[68:69]
	v_mov_b32_e32 v68, v54
	v_mov_b32_e32 v69, v58
	v_pk_fma_f32 v[70:71], v[68:69], v[68:69], v[70:71]
	v_mov_b32_e32 v68, v55
	v_mov_b32_e32 v69, v59
	v_pk_fma_f32 v[44:45], v[68:69], v[68:69], v[70:71]
	s_nop 0
	v_add_f32_e32 v35, v44, v45
	v_mov_b32_e32 v48, v61
	v_mov_b32_e32 v49, v65
	v_mov_b32_e32 v46, v60
	v_mov_b32_e32 v47, v64
	v_pk_mul_f32 v[48:49], v[48:49], v[48:49]
	s_nop 0
	v_pk_fma_f32 v[46:47], v[46:47], v[46:47], v[48:49]
	v_mov_b32_e32 v48, v62
	v_mov_b32_e32 v49, v66
	v_pk_fma_f32 v[46:47], v[48:49], v[48:49], v[46:47]
	v_mov_b32_e32 v48, v63
	v_mov_b32_e32 v49, v67
	v_pk_fma_f32 v[46:47], v[48:49], v[48:49], v[46:47]
	s_nop 0
	v_add_f32_e32 v35, v35, v46
	v_add_f32_e32 v35, v35, v47
	ds_bpermute_b32 v44, v0, v35
	s_waitcnt lgkmcnt(0)
	v_add_f32_e32 v35, v35, v44
	ds_bpermute_b32 v44, v30, v35
	s_waitcnt lgkmcnt(0)
	v_add_f32_e32 v35, v35, v44
	ds_bpermute_b32 v44, v31, v35
	s_waitcnt lgkmcnt(0)
	v_add_f32_e32 v35, v35, v44
	ds_bpermute_b32 v44, v32, v35
	s_waitcnt lgkmcnt(0)
	v_add_f32_e32 v35, v35, v44
	ds_bpermute_b32 v44, v33, v35
	s_waitcnt lgkmcnt(0)
	v_add_f32_e32 v35, v35, v44
	ds_bpermute_b32 v44, v34, v35
	s_waitcnt lgkmcnt(0)
	v_add_f32_e32 v35, v35, v44
	v_fmamk_f32 v35, v35, 0x3a800000, v244
	v_cmp_gt_f32_e32 vcc, s82, v35
	v_mul_f32_e32 v44, 0x4b800000, v35
	s_nop 0
	v_cndmask_b32_e32 v35, v35, v44, vcc
	v_rsq_f32_e32 v35, v35
	s_nop 0
	v_mul_f32_e32 v44, 0x45800000, v35
	v_cndmask_b32_e32 v44, v35, v44, vcc
	v_pk_mul_f32 v[52:53], v[52:53], v[44:45] op_sel_hi:[1,0]
	v_pk_mul_f32 v[54:55], v[54:55], v[44:45] op_sel_hi:[1,0]
	v_pk_mul_f32 v[56:57], v[56:57], v[44:45] op_sel_hi:[1,0]
	v_pk_mul_f32 v[58:59], v[58:59], v[44:45] op_sel_hi:[1,0]
	v_pk_mul_f32 v[60:61], v[60:61], v[44:45] op_sel_hi:[1,0]
	v_pk_mul_f32 v[62:63], v[62:63], v[44:45] op_sel_hi:[1,0]
	v_pk_mul_f32 v[64:65], v[64:65], v[44:45] op_sel_hi:[1,0]
	v_pk_mul_f32 v[66:67], v[66:67], v[44:45] op_sel_hi:[1,0]
	v_pk_mul_f32 v[52:53], v[2:3], v[52:53]
	v_pk_mul_f32 v[54:55], v[4:5], v[54:55]
	v_pk_mul_f32 v[56:57], v[6:7], v[56:57]
	v_pk_mul_f32 v[58:59], v[8:9], v[58:59]
	v_pk_mul_f32 v[60:61], v[10:11], v[60:61]
	v_pk_mul_f32 v[62:63], v[12:13], v[62:63]
	v_pk_mul_f32 v[64:65], v[14:15], v[64:65]
	v_pk_mul_f32 v[66:67], v[16:17], v[66:67]
	v_cvt_pk_bf16_f32 v52, v52, v53
	v_cvt_pk_bf16_f32 v53, v54, v55
	v_cvt_pk_bf16_f32 v54, v56, v57
	v_cvt_pk_bf16_f32 v55, v58, v59
	v_cvt_pk_bf16_f32 v60, v60, v61
	v_cvt_pk_bf16_f32 v61, v62, v63
	v_cvt_pk_bf16_f32 v62, v64, v65
	v_cvt_pk_bf16_f32 v63, v66, v67
	v_add_co_u32_e32 v72, vcc, s83, v26
	s_nop 0
	v_addc_co_u32_e32 v73, vcc, -1, v27, vcc
	global_store_dwordx4 v[72:73], v[52:55], off
	global_store_dwordx4 v[26:27], v[60:63], off
	v_lshl_add_u64 v[26:27], v[26:27], 0, s[68:69]
	s_cbranch_scc1 .LBB0_946
.Lrn8_exit:
.LBB0_947:
	s_add_i32 s40, s41, 9
	s_cmp_lt_i32 s40, s59
	s_cselect_b64 s[44:45], -1, 0
	s_and_b64 s[0:1], s[0:1], s[44:45]
	s_andn2_b64 vcc, exec, s[0:1]
	s_cbranch_vccnz .LBB0_993
	s_mov_b64 s[0:1], s[56:57]
	v_mbcnt_lo_u32_b32 v0, -1, 0
	v_mbcnt_hi_u32_b32 v0, -1, v0
	s_waitcnt vmcnt(0) lgkmcnt(0)
	v_mov_b64_e32 v[2:3], s[0:1]
	global_load_dwordx2 v[2:3], v[2:3], off offset:216
	s_waitcnt vmcnt(0)
	v_cmp_eq_u32_e32 vcc, 0, v0
	s_and_b64 s[4:5], s[76:77], vcc
	s_waitcnt lgkmcnt(0)
	s_barrier
	s_and_saveexec_b64 s[0:1], s[4:5]
	s_cbranch_execz .LBB0_992
	v_readlane_b32 s5, v254, 58
	s_getreg_b32 s4, hwreg(HW_REG_XCC_ID, 0, 4)
	s_waitcnt vmcnt(0) expcnt(0) lgkmcnt(0)
	v_mov_b32_e32 v0, s5
	ds_read_b32 v6, v0
	v_readlane_b32 s5, v254, 59
	s_and_b32 s41, s4, 15
	s_waitcnt lgkmcnt(0)
	v_cmp_ne_u32_e32 vcc, 0, v6
	v_mov_b32_e32 v0, s5
	ds_read_b32 v0, v0
	s_cbranch_vccnz .LBB0_963
	s_mov_b64 s[4:5], 0x1eb89200
	v_lshl_add_u64 v[4:5], v[2:3], 0, s[4:5]
	s_mov_b64 s[4:5], 0x1eb89400
	v_lshl_add_u64 v[6:7], v[2:3], 0, s[4:5]
	s_mov_b64 s[4:5], 0x1eb89500
	v_lshl_add_u64 v[8:9], v[2:3], 0, s[4:5]
	s_mov_b64 s[4:5], 0x1eb89600
	v_lshl_add_u64 v[10:11], v[2:3], 0, s[4:5]
	s_mov_b64 s[4:5], 0x1eb89700
	v_lshl_add_u64 v[12:13], v[2:3], 0, s[4:5]
	s_mov_b64 s[4:5], 0x1eb89800
	v_lshl_add_u64 v[14:15], v[2:3], 0, s[4:5]
	s_mov_b64 s[4:5], 0x1eb89900
	v_lshl_add_u64 v[16:17], v[2:3], 0, s[4:5]
	s_mov_b64 s[4:5], 0x1eb89a00
	v_lshl_add_u64 v[18:19], v[2:3], 0, s[4:5]
	s_mov_b64 s[4:5], 0x1eb89b00
	v_lshl_add_u64 v[20:21], v[2:3], 0, s[4:5]
	s_mov_b64 s[4:5], 0x1eb89c00
	v_lshl_add_u64 v[22:23], v[2:3], 0, s[4:5]
	s_mov_b64 s[4:5], 0x1eb89d00
	v_lshl_add_u64 v[24:25], v[2:3], 0, s[4:5]
	s_mov_b64 s[4:5], 0x1eb89e00
	v_lshl_add_u64 v[26:27], v[2:3], 0, s[4:5]
	s_mov_b64 s[4:5], 0x1eb89f00
	v_lshl_add_u64 v[28:29], v[2:3], 0, s[4:5]
	s_mov_b64 s[4:5], 0x1eb8a000
	v_lshl_add_u64 v[30:31], v[2:3], 0, s[4:5]
	s_mov_b64 s[4:5], 0x1eb8a100
	v_lshl_add_u64 v[32:33], v[2:3], 0, s[4:5]
	s_mov_b64 s[4:5], 0x1eb8a200
	v_lshl_add_u64 v[34:35], v[2:3], 0, s[4:5]
	s_mov_b64 s[4:5], 0x1eb8a300
	v_lshl_add_u64 v[36:37], v[2:3], 0, s[4:5]
	s_mov_b32 s24, 1
	s_mov_b64 s[4:5], 0
	s_branch .LBB0_953
